# attention PV section: 4 packed f32 adds beside the MFMAs split into scalar adds (bit-identical)
# speedup vs baseline: 1.0071x; 1.0012x over previous
; template <int DK, bool PF>
; DEV void attn_item(const u16* __restrict__ qrow, const u16* __restrict__ ka, int ldka, const u16* __restrict__ kb, int ldkb,
;                    const u16* __restrict__ vt, int ldvt, int ntiles, int my_tiles, int kvlen, u16* orow,
;                    unsigned char* smem) {
;     ...
;         union { bf16x8 v[2]; unsigned u[8]; } pfu;
;         float ps = 0.f;
; #pragma unroll
;         for (int r = 0; r < 16; r += 2) {
;           float p0 = __builtin_amdgcn_exp2f(s[r] - mrun);
;           float p1 = __builtin_amdgcn_exp2f(s[r + 1] - mrun);
;           ps += p0 + p1;
;           pfu.u[r >> 1] = pk2bf(p0, p1);
;         }
;         lrun += ps;
; #pragma unroll
;         for (int oc = 0; oc < 2; ++oc)
; #pragma unroll
;           for (int d = 0; d < 4; ++d) o[d] = __builtin_amdgcn_mfma_f32_32x32x16_bf16(vf[oc * 4 + d], pfu.v[oc], o[d], 0, 0, 0);
;       }
.LBB0_1020:
	v_sub_f32_e32 v64, v64, v219
	v_exp_f32_e32 v223, v64
	v_sub_f32_e32 v64, v65, v219
	v_exp_f32_e32 v227, v64
	v_sub_f32_e32 v64, v66, v219
	v_exp_f32_e32 v222, v64
	v_sub_f32_e32 v64, v67, v219
	v_exp_f32_e32 v226, v64
	v_sub_f32_e32 v64, v68, v219
	v_exp_f32_e32 v229, v64
	v_sub_f32_e32 v64, v69, v219
	v_exp_f32_e32 v69, v64
	v_sub_f32_e32 v64, v70, v219
	v_exp_f32_e32 v228, v64
	v_sub_f32_e32 v64, v71, v219
	v_exp_f32_e32 v68, v64
	v_sub_f32_e32 v70, v72, v219
	v_cvt_pk_bf16_f32 v64, v223, v227
	v_cvt_pk_bf16_f32 v65, v222, v226
	v_cvt_pk_bf16_f32 v66, v229, v69
	v_cvt_pk_bf16_f32 v67, v228, v68
	v_exp_f32_e32 v71, v70
	v_sub_f32_e32 v70, v73, v219
	v_mfma_f32_32x32x16_bf16 v[48:63], v[192:195], v[64:67], v[48:63]
	v_exp_f32_e32 v73, v70
	v_sub_f32_e32 v70, v74, v219
	v_sub_f32_e32 v74, v76, v219
	v_sub_f32_e32 v72, v75, v219
	v_exp_f32_e32 v75, v74
	v_sub_f32_e32 v74, v77, v219
	v_exp_f32_e32 v77, v74
	v_mfma_f32_32x32x16_bf16 v[32:47], v[196:199], v[64:67], v[32:47]
	v_sub_f32_e32 v74, v78, v219
	v_exp_f32_e32 v70, v70
	v_exp_f32_e32 v72, v72
	v_exp_f32_e32 v74, v74
	v_add_f32_e32 v68, v228, v68
	v_add_f32_e32 v69, v229, v69
	s_xor_b64 s[10:11], s[10:11], -1
	s_mov_b32 s13, 32
	v_mfma_f32_32x32x16_bf16 v[16:31], v[188:191], v[64:67], v[16:31]
	s_andn2_b64 vcc, exec, s[10:11]
	s_mov_b64 s[10:11], 0
	v_mfma_f32_32x32x16_bf16 v[0:15], v[184:187], v[64:67], v[0:15]
	v_sub_f32_e32 v64, v79, v219
	v_exp_f32_e32 v76, v64
	v_add_f32_e32 v78, v222, v226
	v_add_f32_e32 v79, v223, v227
	v_cvt_pk_bf16_f32 v64, v71, v73
	v_cvt_pk_bf16_f32 v65, v70, v72
	v_cvt_pk_bf16_f32 v66, v75, v77
	v_cvt_pk_bf16_f32 v67, v74, v76
	v_add_f32_e32 v70, v70, v72
	v_add_f32_e32 v71, v71, v73
	v_add_f32_e32 v72, v74, v76
	v_add_f32_e32 v73, v75, v77
	v_add_f32_e32 v74, 0, v79
	v_mfma_f32_32x32x16_bf16 v[48:63], v[176:179], v[64:67], v[48:63]
	v_add_f32_e32 v74, v78, v74
	v_add_f32_e32 v69, v69, v74
	v_add_f32_e32 v68, v68, v69
	v_add_f32_e32 v68, v71, v68
	v_add_f32_e32 v68, v70, v68
	v_add_f32_e32 v68, v73, v68
	v_add_f32_e32 v68, v72, v68
	v_mfma_f32_32x32x16_bf16 v[32:47], v[180:183], v[64:67], v[32:47]
	v_add_f32_e32 v215, v215, v68
	v_mfma_f32_32x32x16_bf16 v[16:31], v[172:175], v[64:67], v[16:31]
	v_mfma_f32_32x32x16_bf16 v[0:15], v[168:171], v[64:67], v[0:15]
	s_cbranch_vccz .LBB0_1023
